# grid barrier: the acquire-side L1 invalidate issued at arrival by wave 1 (all payload loads drained, only sc1 flag traffic follows) instead of after the release flag, 17 barrier sites
# speedup vs baseline: 1.0224x; 1.0224x over previous
; __device__ __forceinline__ unsigned xb_ld(unsigned* p)              { return __hip_atomic_load(p, __ATOMIC_RELAXED, __HIP_MEMORY_SCOPE_AGENT); }
; #define XB_SPIN(cond, bar) do { unsigned _sp = 0; while (cond) { __builtin_amdgcn_s_sleep(1); \
;     if ((++_sp & 255u) == 0u) { if (xb_ld(&(bar)[XB_TMO])) break; if (_sp > XB_SPIN_CAP) { atomicAdd(&(bar)[XB_TMO], 1u); break; } } } } while (0)
; __device__ __forceinline__ void xcd_barrier(const XcdBarrier& b) {
;     ...
;             XB_SPIN(xb_ld(&bar[XB_XGEN(b.x)]) == gen, bar);
;             __builtin_amdgcn_fence(__ATOMIC_ACQUIRE, "agent");
;             asm volatile("s_waitcnt vmcnt(0)" ::: "memory");
.LBB0_201:
	s_or_b64 exec, exec, s[16:17]
	s_waitcnt vmcnt(0)
	s_waitcnt vmcnt(0)

; __device__ __forceinline__ unsigned xb_ld(unsigned* p)              { return __hip_atomic_load(p, __ATOMIC_RELAXED, __HIP_MEMORY_SCOPE_AGENT); }
; __device__ __forceinline__ unsigned xb_add(unsigned* p, unsigned v) { return __hip_atomic_fetch_add(p, v, __ATOMIC_RELAXED, __HIP_MEMORY_SCOPE_AGENT); }
; #define XB_SPIN(cond, bar) do { unsigned _sp = 0; while (cond) { __builtin_amdgcn_s_sleep(1); \
;     if ((++_sp & 255u) == 0u) { if (xb_ld(&(bar)[XB_TMO])) break; if (_sp > XB_SPIN_CAP) { atomicAdd(&(bar)[XB_TMO], 1u); break; } } } } while (0)
; __device__ __forceinline__ void xcd_barrier(const XcdBarrier& b) {
;     ...
;             __builtin_amdgcn_fence(__ATOMIC_RELEASE, "agent");
;             asm volatile("s_waitcnt vmcnt(0)" ::: "memory");
;             const unsigned og = xb_add(&bar[XB_TOP], 1u);
;             const unsigned tg = og / nx;
;             if (og + 1u == (tg + 1u) * nx) xb_add(&bar[XB_TOPGEN], 1u);
;             else XB_SPIN(xb_ld(&bar[XB_TOPGEN]) == tg, bar);
;             __builtin_amdgcn_fence(__ATOMIC_ACQUIRE, "agent");
;             xb_add(&bar[XB_XGEN(b.x)], 1u);
;             asm volatile("s_waitcnt vmcnt(0)" ::: "memory");
;         } else {
;             XB_SPIN(xb_ld(&bar[XB_XGEN(b.x)]) == gen, bar);
;             __builtin_amdgcn_fence(__ATOMIC_ACQUIRE, "agent");
;             asm volatile("s_waitcnt vmcnt(0)" ::: "memory");
;         }
;     }
.LBB0_219:
	s_or_b64 exec, exec, s[8:9]
	s_mov_b64 s[8:9], exec
	v_mbcnt_lo_u32_b32 v0, s8, 0
	v_mbcnt_hi_u32_b32 v0, s9, v0
	v_cmp_eq_u32_e32 vcc, 0, v0
	s_waitcnt vmcnt(0)
	s_and_saveexec_b64 s[14:15], vcc
	s_cbranch_execz .LBB0_221
	s_bcnt1_i32_b64 s3, s[8:9]
	v_mov_b32_e32 v0, 0x2000
	v_mov_b32_e32 v1, s3
	global_atomic_add v0, v1, s[10:11] offset:1024
.LBB0_221:
	s_or_b64 exec, exec, s[14:15]
	s_waitcnt vmcnt(0)
	s_branch .LBB0_222
.Lgsinv_0:
	s_mov_b64 exec, s[6:7]
	v_readfirstlane_b32 s4, v176
	s_cmp_lg_u32 s4, 64
	s_cbranch_scc1 .LBB0_222
	buffer_inv sc1
	s_waitcnt vmcnt(0)

; __device__ __forceinline__ unsigned xb_ld(unsigned* p)              { return __hip_atomic_load(p, __ATOMIC_RELAXED, __HIP_MEMORY_SCOPE_AGENT); }
; #define XB_SPIN(cond, bar) do { unsigned _sp = 0; while (cond) { __builtin_amdgcn_s_sleep(1); \
;     if ((++_sp & 255u) == 0u) { if (xb_ld(&(bar)[XB_TMO])) break; if (_sp > XB_SPIN_CAP) { atomicAdd(&(bar)[XB_TMO], 1u); break; } } } } while (0)
; __device__ __forceinline__ void xcd_barrier(const XcdBarrier& b) {
;     ...
;             XB_SPIN(xb_ld(&bar[XB_XGEN(b.x)]) == gen, bar);
;             __builtin_amdgcn_fence(__ATOMIC_ACQUIRE, "agent");
;             asm volatile("s_waitcnt vmcnt(0)" ::: "memory");
.LBB0_453:
	s_or_b64 exec, exec, s[18:19]
	s_waitcnt vmcnt(0)
	s_waitcnt vmcnt(0)

; __device__ __forceinline__ unsigned xb_ld(unsigned* p)              { return __hip_atomic_load(p, __ATOMIC_RELAXED, __HIP_MEMORY_SCOPE_AGENT); }
; __device__ __forceinline__ unsigned xb_add(unsigned* p, unsigned v) { return __hip_atomic_fetch_add(p, v, __ATOMIC_RELAXED, __HIP_MEMORY_SCOPE_AGENT); }
; #define XB_SPIN(cond, bar) do { unsigned _sp = 0; while (cond) { __builtin_amdgcn_s_sleep(1); \
;     if ((++_sp & 255u) == 0u) { if (xb_ld(&(bar)[XB_TMO])) break; if (_sp > XB_SPIN_CAP) { atomicAdd(&(bar)[XB_TMO], 1u); break; } } } } while (0)
; __device__ __forceinline__ void xcd_barrier(const XcdBarrier& b) {
;     ...
;             const unsigned og = xb_add(&bar[XB_TOP], 1u);
;             const unsigned tg = og / nx;
;             if (og + 1u == (tg + 1u) * nx) xb_add(&bar[XB_TOPGEN], 1u);
;             else XB_SPIN(xb_ld(&bar[XB_TOPGEN]) == tg, bar);
;             __builtin_amdgcn_fence(__ATOMIC_ACQUIRE, "agent");
;             xb_add(&bar[XB_XGEN(b.x)], 1u);
;             asm volatile("s_waitcnt vmcnt(0)" ::: "memory");
.LBB0_471:
	s_or_b64 exec, exec, s[8:9]
	s_mov_b64 s[8:9], exec
	v_mbcnt_lo_u32_b32 v0, s8, 0
	v_mbcnt_hi_u32_b32 v0, s9, v0
	v_cmp_eq_u32_e32 vcc, 0, v0
	s_waitcnt vmcnt(0)
	s_and_saveexec_b64 s[16:17], vcc
	s_cbranch_execz .LBB0_473
	s_bcnt1_i32_b64 s3, s[8:9]
	v_mov_b32_e32 v0, 0x2000
	v_mov_b32_e32 v1, s3
	global_atomic_add v0, v1, s[10:11] offset:1024
.LBB0_473:
	s_or_b64 exec, exec, s[16:17]
	s_waitcnt vmcnt(0)
	s_branch .LBB0_474

; __device__ __forceinline__ unsigned xb_ld(unsigned* p)              { return __hip_atomic_load(p, __ATOMIC_RELAXED, __HIP_MEMORY_SCOPE_AGENT); }
; #define XB_SPIN(cond, bar) do { unsigned _sp = 0; while (cond) { __builtin_amdgcn_s_sleep(1); \
;     if ((++_sp & 255u) == 0u) { if (xb_ld(&(bar)[XB_TMO])) break; if (_sp > XB_SPIN_CAP) { atomicAdd(&(bar)[XB_TMO], 1u); break; } } } } while (0)
; __device__ __forceinline__ void xcd_barrier(const XcdBarrier& b) {
;     ...
;             XB_SPIN(xb_ld(&bar[XB_XGEN(b.x)]) == gen, bar);
;             __builtin_amdgcn_fence(__ATOMIC_ACQUIRE, "agent");
;             asm volatile("s_waitcnt vmcnt(0)" ::: "memory");
.LBB0_522:
	s_or_b64 exec, exec, s[22:23]
	s_waitcnt vmcnt(0)
	s_waitcnt vmcnt(0)

; __device__ __forceinline__ unsigned xb_ld(unsigned* p)              { return __hip_atomic_load(p, __ATOMIC_RELAXED, __HIP_MEMORY_SCOPE_AGENT); }
; __device__ __forceinline__ unsigned xb_add(unsigned* p, unsigned v) { return __hip_atomic_fetch_add(p, v, __ATOMIC_RELAXED, __HIP_MEMORY_SCOPE_AGENT); }
; #define XB_SPIN(cond, bar) do { unsigned _sp = 0; while (cond) { __builtin_amdgcn_s_sleep(1); \
;     if ((++_sp & 255u) == 0u) { if (xb_ld(&(bar)[XB_TMO])) break; if (_sp > XB_SPIN_CAP) { atomicAdd(&(bar)[XB_TMO], 1u); break; } } } } while (0)
; __device__ __forceinline__ void xcd_barrier(const XcdBarrier& b) {
;     ...
;             const unsigned og = xb_add(&bar[XB_TOP], 1u);
;             const unsigned tg = og / nx;
;             if (og + 1u == (tg + 1u) * nx) xb_add(&bar[XB_TOPGEN], 1u);
;             else XB_SPIN(xb_ld(&bar[XB_TOPGEN]) == tg, bar);
;             __builtin_amdgcn_fence(__ATOMIC_ACQUIRE, "agent");
;             xb_add(&bar[XB_XGEN(b.x)], 1u);
.LBB0_540:
	s_or_b64 exec, exec, s[8:9]
	s_mov_b64 s[8:9], exec
	v_mbcnt_lo_u32_b32 v0, s8, 0
	v_mbcnt_hi_u32_b32 v0, s9, v0
	v_cmp_eq_u32_e32 vcc, 0, v0
	s_waitcnt vmcnt(0)
	s_and_saveexec_b64 s[16:17], vcc
	s_cbranch_execz .LBB0_542
	s_bcnt1_i32_b64 s4, s[8:9]
	v_mov_b32_e32 v0, s4
	v_mov_b32_e32 v1, 0x2000
	global_atomic_add v1, v0, s[10:11] offset:1024

; __device__ __forceinline__ unsigned xb_ld(unsigned* p)              { return __hip_atomic_load(p, __ATOMIC_RELAXED, __HIP_MEMORY_SCOPE_AGENT); }
; __device__ __forceinline__ unsigned xb_add(unsigned* p, unsigned v) { return __hip_atomic_fetch_add(p, v, __ATOMIC_RELAXED, __HIP_MEMORY_SCOPE_AGENT); }
; #define XB_SPIN(cond, bar) do { unsigned _sp = 0; while (cond) { __builtin_amdgcn_s_sleep(1); \
;     if ((++_sp & 255u) == 0u) { if (xb_ld(&(bar)[XB_TMO])) break; if (_sp > XB_SPIN_CAP) { atomicAdd(&(bar)[XB_TMO], 1u); break; } } } } while (0)
; __device__ __forceinline__ void xcd_barrier(const XcdBarrier& b) {
;     asm volatile("s_waitcnt vmcnt(0)" ::: "memory");
;     __syncthreads();
;     if (threadIdx.x == 0) {
;         unsigned* bar = b.bar;
;         __builtin_amdgcn_s_waitcnt(0);
;         unsigned nloc = b.st[0], nx = b.st[1];
;         if (nloc == 0u) { xcd_barrier_complete(bar, b.x, nloc, nx); b.st[0] = nloc; b.st[1] = nx; }
;         const unsigned old = xb_add(&bar[XB_XSUB(b.x)], 1u);
;         const unsigned gen = old / nloc;
;         if (old + 1u == (gen + 1u) * nloc) {
;             __builtin_amdgcn_fence(__ATOMIC_RELEASE, "agent");
;             asm volatile("s_waitcnt vmcnt(0)" ::: "memory");
;             const unsigned og = xb_add(&bar[XB_TOP], 1u);
;             const unsigned tg = og / nx;
;             if (og + 1u == (tg + 1u) * nx) xb_add(&bar[XB_TOPGEN], 1u);
;             else XB_SPIN(xb_ld(&bar[XB_TOPGEN]) == tg, bar);
;             __builtin_amdgcn_fence(__ATOMIC_ACQUIRE, "agent");
;             xb_add(&bar[XB_XGEN(b.x)], 1u);
;             asm volatile("s_waitcnt vmcnt(0)" ::: "memory");
;         } else {
;             XB_SPIN(xb_ld(&bar[XB_XGEN(b.x)]) == gen, bar);
;             __builtin_amdgcn_fence(__ATOMIC_ACQUIRE, "agent");
;             asm volatile("s_waitcnt vmcnt(0)" ::: "memory");
;         }
;     }
;     __syncthreads();
; }
.Lgsinv_4:
	s_mov_b64 exec, s[6:7]
	v_readfirstlane_b32 s10, v176
	s_cmp_lg_u32 s10, 64
	s_cbranch_scc1 .LBB0_543
	buffer_inv sc1
	s_waitcnt vmcnt(0)

; __device__ __forceinline__ unsigned xb_ld(unsigned* p)              { return __hip_atomic_load(p, __ATOMIC_RELAXED, __HIP_MEMORY_SCOPE_AGENT); }
; __device__ __forceinline__ unsigned xb_add(unsigned* p, unsigned v) { return __hip_atomic_fetch_add(p, v, __ATOMIC_RELAXED, __HIP_MEMORY_SCOPE_AGENT); }
; #define XB_SPIN(cond, bar) do { unsigned _sp = 0; while (cond) { __builtin_amdgcn_s_sleep(1); \
;     if ((++_sp & 255u) == 0u) { if (xb_ld(&(bar)[XB_TMO])) break; if (_sp > XB_SPIN_CAP) { atomicAdd(&(bar)[XB_TMO], 1u); break; } } } } while (0)
; __device__ __forceinline__ void xcd_barrier(const XcdBarrier& b) {
;     ...
;             const unsigned og = xb_add(&bar[XB_TOP], 1u);
;             const unsigned tg = og / nx;
;             if (og + 1u == (tg + 1u) * nx) xb_add(&bar[XB_TOPGEN], 1u);
;             else XB_SPIN(xb_ld(&bar[XB_TOPGEN]) == tg, bar);
;             __builtin_amdgcn_fence(__ATOMIC_ACQUIRE, "agent");
;             xb_add(&bar[XB_XGEN(b.x)], 1u);
;             asm volatile("s_waitcnt vmcnt(0)" ::: "memory");
;         } else {
;             XB_SPIN(xb_ld(&bar[XB_XGEN(b.x)]) == gen, bar);
;             __builtin_amdgcn_fence(__ATOMIC_ACQUIRE, "agent");
;             asm volatile("s_waitcnt vmcnt(0)" ::: "memory");
;         }
;     }
.LBB0_648:
	s_or_b64 exec, exec, s[16:17]
	s_mov_b64 s[16:17], exec
	v_mbcnt_lo_u32_b32 v0, s16, 0
	v_mbcnt_hi_u32_b32 v0, s17, v0
	v_cmp_eq_u32_e32 vcc, 0, v0
	s_waitcnt vmcnt(0)
	s_and_saveexec_b64 s[22:23], vcc
	s_cbranch_execz .LBB0_650
	s_bcnt1_i32_b64 s4, s[16:17]
	v_mov_b32_e32 v0, s4
	v_mov_b32_e32 v1, 0x2000
	global_atomic_add v1, v0, s[38:39] offset:1024
.LBB0_650:
	s_or_b64 exec, exec, s[22:23]
	s_waitcnt vmcnt(0)
	s_branch .LBB0_651
.Lgsinv_5:
	s_mov_b64 exec, s[8:9]
	v_readfirstlane_b32 s14, v176
	s_cmp_lg_u32 s14, 64
	s_cbranch_scc1 .LBB0_651
	buffer_inv sc1
	s_waitcnt vmcnt(0)

; __device__ __forceinline__ unsigned xb_ld(unsigned* p)              { return __hip_atomic_load(p, __ATOMIC_RELAXED, __HIP_MEMORY_SCOPE_AGENT); }
; __device__ __forceinline__ unsigned xb_add(unsigned* p, unsigned v) { return __hip_atomic_fetch_add(p, v, __ATOMIC_RELAXED, __HIP_MEMORY_SCOPE_AGENT); }
; #define XB_SPIN(cond, bar) do { unsigned _sp = 0; while (cond) { __builtin_amdgcn_s_sleep(1); \
;     if ((++_sp & 255u) == 0u) { if (xb_ld(&(bar)[XB_TMO])) break; if (_sp > XB_SPIN_CAP) { atomicAdd(&(bar)[XB_TMO], 1u); break; } } } } while (0)
; __device__ __forceinline__ void xcd_barrier(const XcdBarrier& b) {
;     ...
;             const unsigned og = xb_add(&bar[XB_TOP], 1u);
;             const unsigned tg = og / nx;
;             if (og + 1u == (tg + 1u) * nx) xb_add(&bar[XB_TOPGEN], 1u);
;             else XB_SPIN(xb_ld(&bar[XB_TOPGEN]) == tg, bar);
;             __builtin_amdgcn_fence(__ATOMIC_ACQUIRE, "agent");
;             xb_add(&bar[XB_XGEN(b.x)], 1u);
.LBB0_736:
	s_or_b64 exec, exec, s[8:9]
	s_mov_b64 s[8:9], exec
	v_mbcnt_lo_u32_b32 v0, s8, 0
	v_mbcnt_hi_u32_b32 v0, s9, v0
	v_cmp_eq_u32_e32 vcc, 0, v0
	s_waitcnt vmcnt(0)
	s_and_saveexec_b64 s[16:17], vcc
	s_cbranch_execz .LBB0_738
	s_bcnt1_i32_b64 s4, s[8:9]
	v_mov_b32_e32 v0, s4
	v_mov_b32_e32 v1, 0x2000
	global_atomic_add v1, v0, s[26:27] offset:1024

; __device__ __forceinline__ unsigned xb_ld(unsigned* p)              { return __hip_atomic_load(p, __ATOMIC_RELAXED, __HIP_MEMORY_SCOPE_AGENT); }
; __device__ __forceinline__ unsigned xb_add(unsigned* p, unsigned v) { return __hip_atomic_fetch_add(p, v, __ATOMIC_RELAXED, __HIP_MEMORY_SCOPE_AGENT); }
; #define XB_SPIN(cond, bar) do { unsigned _sp = 0; while (cond) { __builtin_amdgcn_s_sleep(1); \
;     if ((++_sp & 255u) == 0u) { if (xb_ld(&(bar)[XB_TMO])) break; if (_sp > XB_SPIN_CAP) { atomicAdd(&(bar)[XB_TMO], 1u); break; } } } } while (0)
; __device__ __forceinline__ void xcd_barrier(const XcdBarrier& b) {
;     asm volatile("s_waitcnt vmcnt(0)" ::: "memory");
;     __syncthreads();
;     if (threadIdx.x == 0) {
;         unsigned* bar = b.bar;
;         __builtin_amdgcn_s_waitcnt(0);
;         unsigned nloc = b.st[0], nx = b.st[1];
;         if (nloc == 0u) { xcd_barrier_complete(bar, b.x, nloc, nx); b.st[0] = nloc; b.st[1] = nx; }
;         const unsigned old = xb_add(&bar[XB_XSUB(b.x)], 1u);
;         const unsigned gen = old / nloc;
;         if (old + 1u == (gen + 1u) * nloc) {
;             __builtin_amdgcn_fence(__ATOMIC_RELEASE, "agent");
;             asm volatile("s_waitcnt vmcnt(0)" ::: "memory");
;             const unsigned og = xb_add(&bar[XB_TOP], 1u);
;             const unsigned tg = og / nx;
;             if (og + 1u == (tg + 1u) * nx) xb_add(&bar[XB_TOPGEN], 1u);
;             else XB_SPIN(xb_ld(&bar[XB_TOPGEN]) == tg, bar);
;             __builtin_amdgcn_fence(__ATOMIC_ACQUIRE, "agent");
;             xb_add(&bar[XB_XGEN(b.x)], 1u);
;             asm volatile("s_waitcnt vmcnt(0)" ::: "memory");
;         } else {
;             XB_SPIN(xb_ld(&bar[XB_XGEN(b.x)]) == gen, bar);
;             __builtin_amdgcn_fence(__ATOMIC_ACQUIRE, "agent");
;             asm volatile("s_waitcnt vmcnt(0)" ::: "memory");
;         }
;     }
;     __syncthreads();
; }
.Lgsinv_6:
	s_mov_b64 exec, s[6:7]
	v_readfirstlane_b32 s14, v176
	s_cmp_lg_u32 s14, 64
	s_cbranch_scc1 .LBB0_739
	buffer_inv sc1
	s_waitcnt vmcnt(0)

; __device__ __forceinline__ unsigned xb_ld(unsigned* p)              { return __hip_atomic_load(p, __ATOMIC_RELAXED, __HIP_MEMORY_SCOPE_AGENT); }
; #define XB_SPIN(cond, bar) do { unsigned _sp = 0; while (cond) { __builtin_amdgcn_s_sleep(1); \
;     if ((++_sp & 255u) == 0u) { if (xb_ld(&(bar)[XB_TMO])) break; if (_sp > XB_SPIN_CAP) { atomicAdd(&(bar)[XB_TMO], 1u); break; } } } } while (0)
; __device__ __forceinline__ void xcd_barrier(const XcdBarrier& b) {
;     ...
;             XB_SPIN(xb_ld(&bar[XB_XGEN(b.x)]) == gen, bar);
;             __builtin_amdgcn_fence(__ATOMIC_ACQUIRE, "agent");
;             asm volatile("s_waitcnt vmcnt(0)" ::: "memory");
.LBB0_943:
	s_or_b64 exec, exec, s[14:15]
	s_waitcnt vmcnt(0)
	s_waitcnt vmcnt(0)

; __device__ __forceinline__ unsigned xb_ld(unsigned* p)              { return __hip_atomic_load(p, __ATOMIC_RELAXED, __HIP_MEMORY_SCOPE_AGENT); }
; __device__ __forceinline__ unsigned xb_add(unsigned* p, unsigned v) { return __hip_atomic_fetch_add(p, v, __ATOMIC_RELAXED, __HIP_MEMORY_SCOPE_AGENT); }
; #define XB_SPIN(cond, bar) do { unsigned _sp = 0; while (cond) { __builtin_amdgcn_s_sleep(1); \
;     if ((++_sp & 255u) == 0u) { if (xb_ld(&(bar)[XB_TMO])) break; if (_sp > XB_SPIN_CAP) { atomicAdd(&(bar)[XB_TMO], 1u); break; } } } } while (0)
; __device__ __forceinline__ void xcd_barrier(const XcdBarrier& b) {
;     ...
;             const unsigned og = xb_add(&bar[XB_TOP], 1u);
;             const unsigned tg = og / nx;
;             if (og + 1u == (tg + 1u) * nx) xb_add(&bar[XB_TOPGEN], 1u);
;             else XB_SPIN(xb_ld(&bar[XB_TOPGEN]) == tg, bar);
;             __builtin_amdgcn_fence(__ATOMIC_ACQUIRE, "agent");
;             xb_add(&bar[XB_XGEN(b.x)], 1u);
;             asm volatile("s_waitcnt vmcnt(0)" ::: "memory");
.LBB0_961:
	s_or_b64 exec, exec, s[8:9]
	s_mov_b64 s[8:9], exec
	v_mbcnt_lo_u32_b32 v0, s8, 0
	v_mbcnt_hi_u32_b32 v0, s9, v0
	v_cmp_eq_u32_e32 vcc, 0, v0
	s_waitcnt vmcnt(0)
	s_and_saveexec_b64 s[12:13], vcc
	s_cbranch_execz .LBB0_963
	s_bcnt1_i32_b64 s4, s[8:9]
	v_mov_b32_e32 v0, 0x2000
	v_mov_b32_e32 v1, s4
	global_atomic_add v0, v1, s[10:11] offset:1024
.LBB0_963:
	s_or_b64 exec, exec, s[12:13]
	s_waitcnt vmcnt(0)
	s_branch .LBB0_964

; __device__ __forceinline__ unsigned xb_ld(unsigned* p)              { return __hip_atomic_load(p, __ATOMIC_RELAXED, __HIP_MEMORY_SCOPE_AGENT); }
; __device__ __forceinline__ unsigned xb_add(unsigned* p, unsigned v) { return __hip_atomic_fetch_add(p, v, __ATOMIC_RELAXED, __HIP_MEMORY_SCOPE_AGENT); }
; #define XB_SPIN(cond, bar) do { unsigned _sp = 0; while (cond) { __builtin_amdgcn_s_sleep(1); \
;     if ((++_sp & 255u) == 0u) { if (xb_ld(&(bar)[XB_TMO])) break; if (_sp > XB_SPIN_CAP) { atomicAdd(&(bar)[XB_TMO], 1u); break; } } } } while (0)
; __device__ __forceinline__ void xcd_barrier(const XcdBarrier& b) {
;     ...
;             const unsigned og = xb_add(&bar[XB_TOP], 1u);
;             const unsigned tg = og / nx;
;             if (og + 1u == (tg + 1u) * nx) xb_add(&bar[XB_TOPGEN], 1u);
;             else XB_SPIN(xb_ld(&bar[XB_TOPGEN]) == tg, bar);
;             __builtin_amdgcn_fence(__ATOMIC_ACQUIRE, "agent");
;             xb_add(&bar[XB_XGEN(b.x)], 1u);
.LBB0_1073:
	s_or_b64 exec, exec, s[10:11]
	s_mov_b64 s[10:11], exec
	v_mbcnt_lo_u32_b32 v0, s10, 0
	v_mbcnt_hi_u32_b32 v0, s11, v0
	v_cmp_eq_u32_e32 vcc, 0, v0
	s_waitcnt vmcnt(0)
	s_and_saveexec_b64 s[14:15], vcc
	s_cbranch_execz .LBB0_1075
	s_bcnt1_i32_b64 s4, s[10:11]
	v_mov_b32_e32 v0, 0x2000
	v_mov_b32_e32 v1, s4
	global_atomic_add v0, v1, s[12:13] offset:1024

; __device__ __forceinline__ unsigned xb_ld(unsigned* p)              { return __hip_atomic_load(p, __ATOMIC_RELAXED, __HIP_MEMORY_SCOPE_AGENT); }
; __device__ __forceinline__ unsigned xb_add(unsigned* p, unsigned v) { return __hip_atomic_fetch_add(p, v, __ATOMIC_RELAXED, __HIP_MEMORY_SCOPE_AGENT); }
; #define XB_SPIN(cond, bar) do { unsigned _sp = 0; while (cond) { __builtin_amdgcn_s_sleep(1); \
;     if ((++_sp & 255u) == 0u) { if (xb_ld(&(bar)[XB_TMO])) break; if (_sp > XB_SPIN_CAP) { atomicAdd(&(bar)[XB_TMO], 1u); break; } } } } while (0)
; __device__ __forceinline__ void xcd_barrier(const XcdBarrier& b) {
;     asm volatile("s_waitcnt vmcnt(0)" ::: "memory");
;     __syncthreads();
;     if (threadIdx.x == 0) {
;         unsigned* bar = b.bar;
;         __builtin_amdgcn_s_waitcnt(0);
;         unsigned nloc = b.st[0], nx = b.st[1];
;         if (nloc == 0u) { xcd_barrier_complete(bar, b.x, nloc, nx); b.st[0] = nloc; b.st[1] = nx; }
;         const unsigned old = xb_add(&bar[XB_XSUB(b.x)], 1u);
;         const unsigned gen = old / nloc;
;         if (old + 1u == (gen + 1u) * nloc) {
;             __builtin_amdgcn_fence(__ATOMIC_RELEASE, "agent");
;             asm volatile("s_waitcnt vmcnt(0)" ::: "memory");
;             const unsigned og = xb_add(&bar[XB_TOP], 1u);
;             const unsigned tg = og / nx;
;             if (og + 1u == (tg + 1u) * nx) xb_add(&bar[XB_TOPGEN], 1u);
;             else XB_SPIN(xb_ld(&bar[XB_TOPGEN]) == tg, bar);
;             __builtin_amdgcn_fence(__ATOMIC_ACQUIRE, "agent");
;             xb_add(&bar[XB_XGEN(b.x)], 1u);
;             asm volatile("s_waitcnt vmcnt(0)" ::: "memory");
;         } else {
;             XB_SPIN(xb_ld(&bar[XB_XGEN(b.x)]) == gen, bar);
;             __builtin_amdgcn_fence(__ATOMIC_ACQUIRE, "agent");
;             asm volatile("s_waitcnt vmcnt(0)" ::: "memory");
;         }
;     }
;     __syncthreads();
; }
.Lgsinv_9:
	s_mov_b64 exec, s[6:7]
	v_readfirstlane_b32 s12, v176
	s_cmp_lg_u32 s12, 64
	s_cbranch_scc1 .LBB0_1076
	buffer_inv sc1
	s_waitcnt vmcnt(0)

; __device__ __forceinline__ unsigned xb_ld(unsigned* p)              { return __hip_atomic_load(p, __ATOMIC_RELAXED, __HIP_MEMORY_SCOPE_AGENT); }
; #define XB_SPIN(cond, bar) do { unsigned _sp = 0; while (cond) { __builtin_amdgcn_s_sleep(1); \
;     if ((++_sp & 255u) == 0u) { if (xb_ld(&(bar)[XB_TMO])) break; if (_sp > XB_SPIN_CAP) { atomicAdd(&(bar)[XB_TMO], 1u); break; } } } } while (0)
; __device__ __forceinline__ void xcd_barrier(const XcdBarrier& b) {
;     ...
;             XB_SPIN(xb_ld(&bar[XB_XGEN(b.x)]) == gen, bar);
;             __builtin_amdgcn_fence(__ATOMIC_ACQUIRE, "agent");
;             asm volatile("s_waitcnt vmcnt(0)" ::: "memory");
.LBB0_1603:
	s_or_b64 exec, exec, s[10:11]
	s_waitcnt vmcnt(0)
	s_waitcnt vmcnt(0)

; __device__ __forceinline__ unsigned xb_ld(unsigned* p)              { return __hip_atomic_load(p, __ATOMIC_RELAXED, __HIP_MEMORY_SCOPE_AGENT); }
; __device__ __forceinline__ unsigned xb_add(unsigned* p, unsigned v) { return __hip_atomic_fetch_add(p, v, __ATOMIC_RELAXED, __HIP_MEMORY_SCOPE_AGENT); }
; #define XB_SPIN(cond, bar) do { unsigned _sp = 0; while (cond) { __builtin_amdgcn_s_sleep(1); \
;     if ((++_sp & 255u) == 0u) { if (xb_ld(&(bar)[XB_TMO])) break; if (_sp > XB_SPIN_CAP) { atomicAdd(&(bar)[XB_TMO], 1u); break; } } } } while (0)
; __device__ __forceinline__ void xcd_barrier(const XcdBarrier& b) {
;     ...
;             const unsigned og = xb_add(&bar[XB_TOP], 1u);
;             const unsigned tg = og / nx;
;             if (og + 1u == (tg + 1u) * nx) xb_add(&bar[XB_TOPGEN], 1u);
;             else XB_SPIN(xb_ld(&bar[XB_TOPGEN]) == tg, bar);
;             __builtin_amdgcn_fence(__ATOMIC_ACQUIRE, "agent");
;             xb_add(&bar[XB_XGEN(b.x)], 1u);
;             asm volatile("s_waitcnt vmcnt(0)" ::: "memory");
;         } else {
;             XB_SPIN(xb_ld(&bar[XB_XGEN(b.x)]) == gen, bar);
;             __builtin_amdgcn_fence(__ATOMIC_ACQUIRE, "agent");
;             asm volatile("s_waitcnt vmcnt(0)" ::: "memory");
;         }
;     }
.LBB0_1621:
	s_or_b64 exec, exec, s[4:5]
	s_mov_b64 s[4:5], exec
	v_mbcnt_lo_u32_b32 v0, s4, 0
	v_mbcnt_hi_u32_b32 v0, s5, v0
	v_cmp_eq_u32_e32 vcc, 0, v0
	s_waitcnt vmcnt(0)
	s_and_saveexec_b64 s[8:9], vcc
	s_cbranch_execz .LBB0_1623
	s_bcnt1_i32_b64 s4, s[4:5]
	v_mov_b32_e32 v0, 0x2000
	v_mov_b32_e32 v1, s4
	global_atomic_add v0, v1, s[6:7] offset:1024
.LBB0_1623:
	s_or_b64 exec, exec, s[8:9]
	s_waitcnt vmcnt(0)
	s_branch .LBB0_1624
.Lgsinv_16:
	s_mov_b64 exec, s[2:3]
	v_readfirstlane_b32 s4, v176
	s_cmp_lg_u32 s4, 64
	s_cbranch_scc1 .LBB0_1624
	buffer_inv sc1
	s_waitcnt vmcnt(0)
